# attention early path: l-sum add tree interleaved between PV/QK MFMAs of the fused block
# baseline (speedup 1.0000x reference)
; #define AT_LAS __attribute__((address_space(3)))
; #define AT_PK(P, B) cvtpk_s(P[B], P[B + 1])
; __device__ __forceinline__ void pv(f32x16 (&o)[2], AT_LAS const char* vp, const u32x4& pw0, const u32x4& pw1, const u32x4& pw2, const u32x4& pw3) {
; #pragma unroll
;     for (int d0 = 0; d0 < 2; ++d0) { s16x4 lo[4], hh[4];
; #pragma unroll
;         for (int ks = 0; ks < 4; ++ks) { lo[ks] = vtr(vp + d0 * 4096 + ks * 1024); hh[ks] = vtr(vp + d0 * 4096 + ks * 1024 + 512); }
;     ...
;         o[d0] = __builtin_amdgcn_mfma_f32_32x32x16_bf16(__builtin_bit_cast(bf16x8, pw0), AT_VF(0), o[d0], 0, 0, 0);
;         o[d0] = __builtin_amdgcn_mfma_f32_32x32x16_bf16(__builtin_bit_cast(bf16x8, pw1), AT_VF(1), o[d0], 0, 0, 0);
;         o[d0] = __builtin_amdgcn_mfma_f32_32x32x16_bf16(__builtin_bit_cast(bf16x8, pw2), AT_VF(2), o[d0], 0, 0, 0);
;         o[d0] = __builtin_amdgcn_mfma_f32_32x32x16_bf16(__builtin_bit_cast(bf16x8, pw3), AT_VF(3), o[d0], 0, 0, 0);
;     ...
;     }
; }
; __device__ __forceinline__ void qkt(f32x16& p0, f32x16& p1, AT_LAS const char* kb, const bf16x8 (&qr)[6], const f32x16& negm) {
;     bf16x8 kf[12];
; #pragma unroll
;     for (int d0 = 0; d0 < 6; ++d0) { kf[2 * d0] = *(AT_LAS const bf16x8*)(kb + d0 * 2048); kf[2 * d0 + 1] = *(AT_LAS const bf16x8*)(kb + d0 * 2048 + 512); }
;     __builtin_amdgcn_sched_barrier(0);
; template <int THRL>
; __device__ __forceinline__ void attn_item(int b, int h, int s, const bf16_t* Q, const bf16_t* KN, const bf16_t* KR, const bf16_t* V, const float* goa  , bf16_t* Y, float* ssqy, AT_LAS char* shm, int wid0) {
;     ...
;                 float sacc = 0.f;
; #pragma unroll
;                 for (int r = 0; r < 16; ++r) { p0[r] = __builtin_amdgcn_exp2f(p0[r]); p1[r] = __builtin_amdgcn_exp2f(p1[r]); sacc += p0[r] + p1[r]; }
;                 l_reg += sacc;
;     ...
;                 pw0 = (u32x4){AT_PK(p0, 0), AT_PK(p0, 2), AT_PK(p0, 4), AT_PK(p0, 6)}; pw1 = (u32x4){AT_PK(p0, 8), AT_PK(p0, 10), AT_PK(p0, 12), AT_PK(p0, 14)};
;                 pw2 = (u32x4){AT_PK(p1, 0), AT_PK(p1, 2), AT_PK(p1, 4), AT_PK(p1, 6)}; pw3 = (u32x4){AT_PK(p1, 8), AT_PK(p1, 10), AT_PK(p1, 12), AT_PK(p1, 14)};
;     ...
;                 if (late) have = true;
;                 else pv(o, vp0 + (t & 3) * VSLOTB, pw0, pw1, pw2, pw3);
;             }
;             if (!late) { if (t + 1 < NT && (jb + 1) <= wq) qkt(p0, p1, kp0 + ((t + 1) & 3) * KSLOTB, qr, negm); }
.LBB13_779:
	v_exp_f32_e32 v18, v18
	v_exp_f32_e32 v34, v34
	v_exp_f32_e32 v0, v19
	v_exp_f32_e32 v154, v35
	v_exp_f32_e32 v20, v20
	v_exp_f32_e32 v36, v36
	v_exp_f32_e32 v168, v21
	v_exp_f32_e32 v156, v37
	v_exp_f32_e32 v22, v22
	v_exp_f32_e32 v38, v38
	v_exp_f32_e32 v170, v23
	v_exp_f32_e32 v158, v39
	v_exp_f32_e32 v24, v24
	v_exp_f32_e32 v40, v40
	v_exp_f32_e32 v172, v25
	v_exp_f32_e32 v160, v41
	v_exp_f32_e32 v26, v26
	v_exp_f32_e32 v42, v42
	v_exp_f32_e32 v174, v27
	v_exp_f32_e32 v162, v43
	v_exp_f32_e32 v28, v28
	v_exp_f32_e32 v44, v44
	v_exp_f32_e32 v176, v29
	v_exp_f32_e32 v164, v45
	v_exp_f32_e32 v30, v30
	v_exp_f32_e32 v46, v46
	v_exp_f32_e32 v178, v31
	v_exp_f32_e32 v166, v47
	v_exp_f32_e32 v32, v32
	v_exp_f32_e32 v48, v48
	v_exp_f32_e32 v33, v33
	v_exp_f32_e32 v49, v49
	v_cvt_pk_bf16_f32 v110, v18, v0
	v_cvt_pk_bf16_f32 v111, v20, v168
	v_cvt_pk_bf16_f32 v112, v22, v170
	v_cvt_pk_bf16_f32 v113, v24, v172
	v_cvt_pk_bf16_f32 v106, v26, v174
	v_cvt_pk_bf16_f32 v107, v28, v176
	v_cvt_pk_bf16_f32 v108, v30, v178
	v_cvt_pk_bf16_f32 v109, v32, v33
	v_cvt_pk_bf16_f32 v118, v34, v154
	v_cvt_pk_bf16_f32 v119, v36, v156
	v_cvt_pk_bf16_f32 v120, v38, v158
	v_cvt_pk_bf16_f32 v121, v40, v160
	v_cvt_pk_bf16_f32 v114, v42, v162
	v_cvt_pk_bf16_f32 v115, v44, v164
	v_cvt_pk_bf16_f32 v116, v46, v166
	s_and_b64 vcc, exec, s[76:77]
	v_cvt_pk_bf16_f32 v117, v48, v49
	s_cbranch_vccnz .LBB13_781
	s_add_i32 s92, s9, -2
	s_cmp_lt_u32 s92, s79
	s_cselect_b64 vcc, -1, 0
	s_cmp_lt_i32 s84, s2
	s_cselect_b64 s[88:89], -1, 0
	s_and_b64 s[88:89], vcc, s[88:89]
	s_andn2_b64 vcc, exec, s[88:89]
	s_cbranch_vccnz .Lat0_e_pvtree
	s_and_b32 s84, s92, 3
	s_mulk_i32 s84, 0x3000
	v_add_u32_e32 v215, s84, v190
	s_waitcnt lgkmcnt(0)
	ds_read_b64_tr_b16 v[248:249], v214 offset:56320
	ds_read_b64_tr_b16 v[250:251], v214 offset:56832
	ds_read_b128 v[198:201], v215 offset:8192
	ds_read_b128 v[202:205], v215 offset:8704
	ds_read_b128 v[206:209], v215 offset:10240
	ds_read_b128 v[210:213], v215 offset:10752
	s_waitcnt lgkmcnt(6)
	v_mfma_f32_32x32x16_bf16 v[50:65], v[110:113], v[216:219], v[50:65]
	v_add_f32_e32 v18, v18, v34
	v_add_f32_e32 v20, v20, v36
	v_add_f32_e32 v22, v22, v38
	v_add_f32_e32 v24, v24, v40
	v_add_u32_e32 v236, s84, v252
	ds_read_b128 v[34:37], v236
	v_mfma_f32_32x32x16_bf16 v[50:65], v[106:109], v[220:223], v[50:65]
	v_add_f32_e32 v26, v26, v42
	v_add_f32_e32 v28, v28, v44
	v_add_f32_e32 v30, v30, v46
	v_add_f32_e32 v32, v32, v48
	v_add_f32_e32 v0, v0, v154
	v_add_f32_e32 v168, v168, v156
	ds_read_b128 v[154:157], v236 offset:4096
	v_mfma_f32_32x32x16_bf16 v[50:65], v[118:121], v[224:227], v[50:65]
	v_add_f32_e32 v170, v170, v158
	v_add_f32_e32 v172, v172, v160
	v_add_u32_e32 v239, s84, v253
	ds_read_b128 v[158:161], v239
	v_add_f32_e32 v174, v174, v162
	v_add_f32_e32 v176, v176, v164
	v_mfma_f32_32x32x16_bf16 v[50:65], v[114:117], v[228:231], v[50:65]
	ds_read_b128 v[162:165], v239 offset:4096
	v_add_f32_e32 v178, v178, v166
	v_add_f32_e32 v33, v33, v49
	v_add_f32_e32 v18, v18, v0
	v_add_f32_e32 v20, v20, v168
	v_mfma_f32_32x32x16_bf16 v[2:17], v[110:113], v[232:235], v[2:17]
	v_add_u32_e32 v236, s84, v254
	ds_read_b128 v[166:169], v236
	v_add_f32_e32 v22, v22, v170
	v_add_f32_e32 v24, v24, v172
	v_mfma_f32_32x32x16_bf16 v[2:17], v[106:109], v[240:243], v[2:17]
	ds_read_b128 v[170:173], v236 offset:4096
	v_add_f32_e32 v26, v26, v174
	v_add_f32_e32 v28, v28, v176
	v_mfma_f32_32x32x16_bf16 v[2:17], v[118:121], v[244:247], v[2:17]
	v_add_u32_e32 v239, s84, v255
	ds_read_b128 v[174:177], v239
	v_add_f32_e32 v30, v30, v178
	v_add_f32_e32 v32, v32, v33
	s_waitcnt lgkmcnt(11)
	v_mfma_f32_32x32x16_bf16 v[2:17], v[114:117], v[248:251], v[2:17]
	ds_read_b128 v[178:181], v239 offset:4096
	v_add_f32_e32 v214, v18, v20
	v_add_f32_e32 v215, v22, v24
	v_add_f32_e32 v236, v26, v28
	v_add_f32_e32 v239, v30, v32
	s_waitcnt lgkmcnt(7)
	v_mfma_f32_32x32x16_bf16 v[18:33], v[34:37], v[82:85], v[66:81]
	v_add_f32_e32 v214, v214, v215
	v_add_f32_e32 v236, v236, v239
	s_waitcnt lgkmcnt(6)
	v_mfma_f32_32x32x16_bf16 v[34:49], v[154:157], v[82:85], v[66:81]
	v_add_f32_e32 v0, v214, v236
	s_waitcnt lgkmcnt(5)
	v_mfma_f32_32x32x16_bf16 v[18:33], v[158:161], v[86:89], v[18:33]
	v_add_f32_e32 v153, v153, v0
	s_waitcnt lgkmcnt(4)
	v_mfma_f32_32x32x16_bf16 v[34:49], v[162:165], v[86:89], v[34:49]
	s_waitcnt lgkmcnt(3)
	v_mfma_f32_32x32x16_bf16 v[18:33], v[166:169], v[90:93], v[18:33]
	s_waitcnt lgkmcnt(2)
	v_mfma_f32_32x32x16_bf16 v[34:49], v[170:173], v[90:93], v[34:49]
	s_waitcnt lgkmcnt(1)
	v_mfma_f32_32x32x16_bf16 v[18:33], v[174:177], v[94:97], v[18:33]
	s_waitcnt lgkmcnt(0)
	v_mfma_f32_32x32x16_bf16 v[34:49], v[178:181], v[94:97], v[34:49]
	v_mfma_f32_32x32x16_bf16 v[18:33], v[198:201], v[98:101], v[18:33]
	v_mfma_f32_32x32x16_bf16 v[34:49], v[202:205], v[98:101], v[34:49]
	v_mfma_f32_32x32x16_bf16 v[18:33], v[206:209], v[102:105], v[18:33]
	v_mfma_f32_32x32x16_bf16 v[34:49], v[210:213], v[102:105], v[34:49]
	s_branch .LBB13_764
.Lat0_e_pvtree:
	v_add_f32_e32 v18, v18, v34
	v_add_f32_e32 v0, v0, v154
	v_add_f32_e32 v20, v20, v36
	v_add_f32_e32 v168, v168, v156
	v_add_f32_e32 v22, v22, v38
	v_add_f32_e32 v170, v170, v158
	v_add_f32_e32 v24, v24, v40
	v_add_f32_e32 v172, v172, v160
	v_add_f32_e32 v26, v26, v42
	v_add_f32_e32 v174, v174, v162
	v_add_f32_e32 v28, v28, v44
	v_add_f32_e32 v176, v176, v164
	v_add_f32_e32 v30, v30, v46
	v_add_f32_e32 v178, v178, v166
	v_add_f32_e32 v32, v32, v48
	v_add_f32_e32 v33, v33, v49
	v_add_f32_e32 v18, v18, v0
	v_add_f32_e32 v20, v20, v168
	v_add_f32_e32 v22, v22, v170
	v_add_f32_e32 v24, v24, v172
	v_add_f32_e32 v26, v26, v174
	v_add_f32_e32 v28, v28, v176
	v_add_f32_e32 v30, v30, v178
	v_add_f32_e32 v32, v32, v33
	v_add_f32_e32 v18, v18, v20
	v_add_f32_e32 v22, v22, v24
	v_add_f32_e32 v26, v26, v28
	v_add_f32_e32 v30, v30, v32
	v_add_f32_e32 v18, v18, v22
	v_add_f32_e32 v26, v26, v30
	v_add_f32_e32 v0, v18, v26
	v_add_f32_e32 v153, v153, v0
.Lat0_e_pvonly:
	s_waitcnt lgkmcnt(0)
	ds_read_b64_tr_b16 v[248:249], v214 offset:56320
	ds_read_b64_tr_b16 v[250:251], v214 offset:56832
	s_waitcnt lgkmcnt(2)
	v_mfma_f32_32x32x16_bf16 v[50:65], v[110:113], v[216:219], v[50:65]
	v_mfma_f32_32x32x16_bf16 v[50:65], v[106:109], v[220:223], v[50:65]
	v_mfma_f32_32x32x16_bf16 v[50:65], v[118:121], v[224:227], v[50:65]
	v_mfma_f32_32x32x16_bf16 v[50:65], v[114:117], v[228:231], v[50:65]
	v_mfma_f32_32x32x16_bf16 v[2:17], v[110:113], v[232:235], v[2:17]
	v_mfma_f32_32x32x16_bf16 v[2:17], v[106:109], v[240:243], v[2:17]
	v_mfma_f32_32x32x16_bf16 v[2:17], v[118:121], v[244:247], v[2:17]
	s_waitcnt lgkmcnt(0)
	v_mfma_f32_32x32x16_bf16 v[2:17], v[114:117], v[248:251], v[2:17]
	s_branch .LBB13_764

; #define AT_LAS __attribute__((address_space(3)))
; #define AT_PK(P, B) cvtpk_s(P[B], P[B + 1])
; __device__ __forceinline__ void pv(f32x16 (&o)[2], AT_LAS const char* vp, const u32x4& pw0, const u32x4& pw1, const u32x4& pw2, const u32x4& pw3) {
; #pragma unroll
;     for (int d0 = 0; d0 < 2; ++d0) { s16x4 lo[4], hh[4];
; #pragma unroll
;         for (int ks = 0; ks < 4; ++ks) { lo[ks] = vtr(vp + d0 * 4096 + ks * 1024); hh[ks] = vtr(vp + d0 * 4096 + ks * 1024 + 512); }
;     ...
;         o[d0] = __builtin_amdgcn_mfma_f32_32x32x16_bf16(__builtin_bit_cast(bf16x8, pw0), AT_VF(0), o[d0], 0, 0, 0);
;         o[d0] = __builtin_amdgcn_mfma_f32_32x32x16_bf16(__builtin_bit_cast(bf16x8, pw1), AT_VF(1), o[d0], 0, 0, 0);
;         o[d0] = __builtin_amdgcn_mfma_f32_32x32x16_bf16(__builtin_bit_cast(bf16x8, pw2), AT_VF(2), o[d0], 0, 0, 0);
;         o[d0] = __builtin_amdgcn_mfma_f32_32x32x16_bf16(__builtin_bit_cast(bf16x8, pw3), AT_VF(3), o[d0], 0, 0, 0);
;     ...
;     }
; }
; __device__ __forceinline__ void qkt(f32x16& p0, f32x16& p1, AT_LAS const char* kb, const bf16x8 (&qr)[6], const f32x16& negm) {
;     bf16x8 kf[12];
; #pragma unroll
;     for (int d0 = 0; d0 < 6; ++d0) { kf[2 * d0] = *(AT_LAS const bf16x8*)(kb + d0 * 2048); kf[2 * d0 + 1] = *(AT_LAS const bf16x8*)(kb + d0 * 2048 + 512); }
;     __builtin_amdgcn_sched_barrier(0);
; template <int THRL>
; __device__ __forceinline__ void attn_item(int b, int h, int s, const bf16_t* Q, const bf16_t* KN, const bf16_t* KR, const bf16_t* V, const float* goa  , bf16_t* Y, float* ssqy, AT_LAS char* shm, int wid0) {
;     ...
;                 float sacc = 0.f;
; #pragma unroll
;                 for (int r = 0; r < 16; ++r) { p0[r] = __builtin_amdgcn_exp2f(p0[r]); p1[r] = __builtin_amdgcn_exp2f(p1[r]); sacc += p0[r] + p1[r]; }
;                 l_reg += sacc;
;     ...
;                 pw0 = (u32x4){AT_PK(p0, 0), AT_PK(p0, 2), AT_PK(p0, 4), AT_PK(p0, 6)}; pw1 = (u32x4){AT_PK(p0, 8), AT_PK(p0, 10), AT_PK(p0, 12), AT_PK(p0, 14)};
;                 pw2 = (u32x4){AT_PK(p1, 0), AT_PK(p1, 2), AT_PK(p1, 4), AT_PK(p1, 6)}; pw3 = (u32x4){AT_PK(p1, 8), AT_PK(p1, 10), AT_PK(p1, 12), AT_PK(p1, 14)};
;     ...
;                 if (late) have = true;
;                 else pv(o, vp0 + (t & 3) * VSLOTB, pw0, pw1, pw2, pw3);
;             }
;             if (!late) { if (t + 1 < NT && (jb + 1) <= wq) qkt(p0, p1, kp0 + ((t + 1) & 3) * KSLOTB, qr, negm); }
.LBB13_1757:
	v_exp_f32_e32 v18, v18
	v_exp_f32_e32 v34, v34
	v_exp_f32_e32 v0, v19
	v_exp_f32_e32 v154, v35
	v_exp_f32_e32 v20, v20
	v_exp_f32_e32 v36, v36
	v_exp_f32_e32 v168, v21
	v_exp_f32_e32 v156, v37
	v_exp_f32_e32 v22, v22
	v_exp_f32_e32 v38, v38
	v_exp_f32_e32 v170, v23
	v_exp_f32_e32 v158, v39
	v_exp_f32_e32 v24, v24
	v_exp_f32_e32 v40, v40
	v_exp_f32_e32 v172, v25
	v_exp_f32_e32 v160, v41
	v_exp_f32_e32 v26, v26
	v_exp_f32_e32 v42, v42
	v_exp_f32_e32 v174, v27
	v_exp_f32_e32 v162, v43
	v_exp_f32_e32 v28, v28
	v_exp_f32_e32 v44, v44
	v_exp_f32_e32 v176, v29
	v_exp_f32_e32 v164, v45
	v_exp_f32_e32 v30, v30
	v_exp_f32_e32 v46, v46
	v_exp_f32_e32 v178, v31
	v_exp_f32_e32 v166, v47
	v_exp_f32_e32 v32, v32
	v_exp_f32_e32 v48, v48
	v_exp_f32_e32 v33, v33
	v_exp_f32_e32 v49, v49
	v_cvt_pk_bf16_f32 v110, v18, v0
	v_cvt_pk_bf16_f32 v111, v20, v168
	v_cvt_pk_bf16_f32 v112, v22, v170
	v_cvt_pk_bf16_f32 v113, v24, v172
	v_cvt_pk_bf16_f32 v106, v26, v174
	v_cvt_pk_bf16_f32 v107, v28, v176
	v_cvt_pk_bf16_f32 v108, v30, v178
	v_cvt_pk_bf16_f32 v109, v32, v33
	v_cvt_pk_bf16_f32 v118, v34, v154
	v_cvt_pk_bf16_f32 v119, v36, v156
	v_cvt_pk_bf16_f32 v120, v38, v158
	v_cvt_pk_bf16_f32 v121, v40, v160
	v_cvt_pk_bf16_f32 v114, v42, v162
	v_cvt_pk_bf16_f32 v115, v44, v164
	v_cvt_pk_bf16_f32 v116, v46, v166
	s_and_b64 vcc, exec, s[76:77]
	v_cvt_pk_bf16_f32 v117, v48, v49
	s_cbranch_vccnz .LBB13_1759
	s_add_i32 s92, s80, -2
	s_cmp_lt_u32 s92, s3
	s_cselect_b64 vcc, -1, 0
	s_cmp_lt_i32 s84, s33
	s_cselect_b64 s[88:89], -1, 0
	s_and_b64 s[88:89], vcc, s[88:89]
	s_andn2_b64 vcc, exec, s[88:89]
	s_cbranch_vccnz .Lat1_e_pvtree
	s_and_b32 s84, s92, 3
	s_mulk_i32 s84, 0x3000
	v_add_u32_e32 v215, s84, v190
	s_waitcnt lgkmcnt(0)
	ds_read_b64_tr_b16 v[248:249], v214 offset:56320
	ds_read_b64_tr_b16 v[250:251], v214 offset:56832
	ds_read_b128 v[198:201], v215 offset:8192
	ds_read_b128 v[202:205], v215 offset:8704
	ds_read_b128 v[206:209], v215 offset:10240
	ds_read_b128 v[210:213], v215 offset:10752
	s_waitcnt lgkmcnt(6)
	v_mfma_f32_32x32x16_bf16 v[50:65], v[110:113], v[216:219], v[50:65]
	v_add_f32_e32 v18, v18, v34
	v_add_f32_e32 v20, v20, v36
	v_add_f32_e32 v22, v22, v38
	v_add_f32_e32 v24, v24, v40
	v_add_u32_e32 v236, s84, v252
	ds_read_b128 v[34:37], v236
	v_mfma_f32_32x32x16_bf16 v[50:65], v[106:109], v[220:223], v[50:65]
	v_add_f32_e32 v26, v26, v42
	v_add_f32_e32 v28, v28, v44
	v_add_f32_e32 v30, v30, v46
	v_add_f32_e32 v32, v32, v48
	v_add_f32_e32 v0, v0, v154
	v_add_f32_e32 v168, v168, v156
	ds_read_b128 v[154:157], v236 offset:4096
	v_mfma_f32_32x32x16_bf16 v[50:65], v[118:121], v[224:227], v[50:65]
	v_add_f32_e32 v170, v170, v158
	v_add_f32_e32 v172, v172, v160
	v_add_u32_e32 v239, s84, v253
	ds_read_b128 v[158:161], v239
	v_add_f32_e32 v174, v174, v162
	v_add_f32_e32 v176, v176, v164
	v_mfma_f32_32x32x16_bf16 v[50:65], v[114:117], v[228:231], v[50:65]
	ds_read_b128 v[162:165], v239 offset:4096
	v_add_f32_e32 v178, v178, v166
	v_add_f32_e32 v33, v33, v49
	v_add_f32_e32 v18, v18, v0
	v_add_f32_e32 v20, v20, v168
	v_mfma_f32_32x32x16_bf16 v[2:17], v[110:113], v[232:235], v[2:17]
	v_add_u32_e32 v236, s84, v254
	ds_read_b128 v[166:169], v236
	v_add_f32_e32 v22, v22, v170
	v_add_f32_e32 v24, v24, v172
	v_mfma_f32_32x32x16_bf16 v[2:17], v[106:109], v[240:243], v[2:17]
	ds_read_b128 v[170:173], v236 offset:4096
	v_add_f32_e32 v26, v26, v174
	v_add_f32_e32 v28, v28, v176
	v_mfma_f32_32x32x16_bf16 v[2:17], v[118:121], v[244:247], v[2:17]
	v_add_u32_e32 v239, s84, v255
	ds_read_b128 v[174:177], v239
	v_add_f32_e32 v30, v30, v178
	v_add_f32_e32 v32, v32, v33
	s_waitcnt lgkmcnt(11)
	v_mfma_f32_32x32x16_bf16 v[2:17], v[114:117], v[248:251], v[2:17]
	ds_read_b128 v[178:181], v239 offset:4096
	v_add_f32_e32 v214, v18, v20
	v_add_f32_e32 v215, v22, v24
	v_add_f32_e32 v236, v26, v28
	v_add_f32_e32 v239, v30, v32
	s_waitcnt lgkmcnt(7)
	v_mfma_f32_32x32x16_bf16 v[18:33], v[34:37], v[82:85], v[66:81]
	v_add_f32_e32 v214, v214, v215
	v_add_f32_e32 v236, v236, v239
	s_waitcnt lgkmcnt(6)
	v_mfma_f32_32x32x16_bf16 v[34:49], v[154:157], v[82:85], v[66:81]
	v_add_f32_e32 v0, v214, v236
	s_waitcnt lgkmcnt(5)
	v_mfma_f32_32x32x16_bf16 v[18:33], v[158:161], v[86:89], v[18:33]
	v_add_f32_e32 v153, v153, v0
	s_waitcnt lgkmcnt(4)
	v_mfma_f32_32x32x16_bf16 v[34:49], v[162:165], v[86:89], v[34:49]
	s_waitcnt lgkmcnt(3)
	v_mfma_f32_32x32x16_bf16 v[18:33], v[166:169], v[90:93], v[18:33]
	s_waitcnt lgkmcnt(2)
	v_mfma_f32_32x32x16_bf16 v[34:49], v[170:173], v[90:93], v[34:49]
	s_waitcnt lgkmcnt(1)
	v_mfma_f32_32x32x16_bf16 v[18:33], v[174:177], v[94:97], v[18:33]
	s_waitcnt lgkmcnt(0)
	v_mfma_f32_32x32x16_bf16 v[34:49], v[178:181], v[94:97], v[34:49]
	v_mfma_f32_32x32x16_bf16 v[18:33], v[198:201], v[98:101], v[18:33]
	v_mfma_f32_32x32x16_bf16 v[34:49], v[202:205], v[98:101], v[34:49]
	v_mfma_f32_32x32x16_bf16 v[18:33], v[206:209], v[102:105], v[18:33]
	v_mfma_f32_32x32x16_bf16 v[34:49], v[210:213], v[102:105], v[34:49]
	s_branch .LBB13_1742
.Lat1_e_pvtree:
	v_add_f32_e32 v18, v18, v34
	v_add_f32_e32 v0, v0, v154
	v_add_f32_e32 v20, v20, v36
	v_add_f32_e32 v168, v168, v156
	v_add_f32_e32 v22, v22, v38
	v_add_f32_e32 v170, v170, v158
	v_add_f32_e32 v24, v24, v40
	v_add_f32_e32 v172, v172, v160
	v_add_f32_e32 v26, v26, v42
	v_add_f32_e32 v174, v174, v162
	v_add_f32_e32 v28, v28, v44
	v_add_f32_e32 v176, v176, v164
	v_add_f32_e32 v30, v30, v46
	v_add_f32_e32 v178, v178, v166
	v_add_f32_e32 v32, v32, v48
	v_add_f32_e32 v33, v33, v49
	v_add_f32_e32 v18, v18, v0
	v_add_f32_e32 v20, v20, v168
	v_add_f32_e32 v22, v22, v170
	v_add_f32_e32 v24, v24, v172
	v_add_f32_e32 v26, v26, v174
	v_add_f32_e32 v28, v28, v176
	v_add_f32_e32 v30, v30, v178
	v_add_f32_e32 v32, v32, v33
	v_add_f32_e32 v18, v18, v20
	v_add_f32_e32 v22, v22, v24
	v_add_f32_e32 v26, v26, v28
	v_add_f32_e32 v30, v30, v32
	v_add_f32_e32 v18, v18, v22
	v_add_f32_e32 v26, v26, v30
	v_add_f32_e32 v0, v18, v26
	v_add_f32_e32 v153, v153, v0
.Lat1_e_pvonly:
	s_waitcnt lgkmcnt(0)
	ds_read_b64_tr_b16 v[248:249], v214 offset:56320
	ds_read_b64_tr_b16 v[250:251], v214 offset:56832
	s_waitcnt lgkmcnt(2)
	v_mfma_f32_32x32x16_bf16 v[50:65], v[110:113], v[216:219], v[50:65]
	v_mfma_f32_32x32x16_bf16 v[50:65], v[106:109], v[220:223], v[50:65]
	v_mfma_f32_32x32x16_bf16 v[50:65], v[118:121], v[224:227], v[50:65]
	v_mfma_f32_32x32x16_bf16 v[50:65], v[114:117], v[228:231], v[50:65]
	v_mfma_f32_32x32x16_bf16 v[2:17], v[110:113], v[232:235], v[2:17]
	v_mfma_f32_32x32x16_bf16 v[2:17], v[106:109], v[240:243], v[2:17]
	v_mfma_f32_32x32x16_bf16 v[2:17], v[118:121], v[244:247], v[2:17]
	s_waitcnt lgkmcnt(0)
	v_mfma_f32_32x32x16_bf16 v[2:17], v[114:117], v[248:251], v[2:17]
	s_branch .LBB13_1742
